# GLA pass C: non-temporal hint on the once-read tile loads (states, q~/k~, v)
# speedup vs baseline: 1.0048x; 1.0048x over previous
.LBB0_505:
	s_ashr_i32 s2, s59, 9
	s_bfe_u32 s62, s59, 0x20007
	s_and_b32 s6, s59, 0x7f
	s_lshl_b32 s3, s2, 13
	s_lshl_b32 s2, s2, 2
	s_lshl_b32 s4, s6, 6
	s_or_b32 s7, s2, s62
	s_or_b32 s8, s4, s3
	s_lshl_b32 s4, s7, 1
	s_add_i32 s2, s6, 4
	s_sub_i32 s5, 0x83, s6
	s_mul_i32 s3, s7, 0x108
	s_mul_hi_i32 s9, s4, 0x84
	s_add_u32 s2, s3, s2
	s_addc_u32 s3, s9, 0
	s_lshl_b64 s[2:3], s[2:3], 14
	s_add_u32 s2, s0, s2
	s_addc_u32 s3, s1, s3
	s_or_b32 s4, s4, 1
	s_mul_hi_i32 s9, s4, 0x84
	s_mulk_i32 s4, 0x84
	s_add_u32 s4, s4, s5
	v_mov_b32_e32 v63, v188
	s_addc_u32 s5, s9, 0
	s_lshl_b64 s[4:5], s[4:5], 14
	v_lshlrev_b32_e32 v28, 4, v63
	v_ashrrev_i32_e32 v47, 4, v63
	s_add_u32 s4, s0, s4
	v_and_b32_e32 v52, 0xf0, v28
	v_add_u32_e32 v0, s8, v47
	s_addc_u32 s5, s1, s5
	v_lshl_add_u64 v[16:17], s[2:3], 0, v[52:53]
	v_mad_i64_i32 v[0:1], s[2:3], v0, s52, v[54:55]
	s_lshl_b32 s46, s62, 8
	v_lshl_add_u64 v[0:1], v[0:1], 0, s[46:47]
	v_lshl_add_u64 v[8:9], v[0:1], 0, v[52:53]
	v_lshlrev_b32_e32 v0, 7, v47
	v_ashrrev_i32_e32 v1, 31, v0
	v_lshlrev_b64 v[10:11], 1, v[0:1]
	v_lshl_add_u64 v[12:13], v[16:17], 0, v[10:11]
	global_load_dwordx4 v[0:3], v[8:9], off offset:1024 nt
	global_load_dwordx4 v[4:7], v[12:13], off nt
	v_add_u32_e32 v8, 0x200, v63
	v_ashrrev_i32_e32 v48, 4, v8
	v_add_u32_e32 v8, s8, v48
	v_lshl_add_u64 v[18:19], s[4:5], 0, v[52:53]
	v_mad_i64_i32 v[8:9], s[2:3], v8, s52, v[54:55]
	v_lshl_add_u64 v[20:21], v[18:19], 0, v[10:11]
	v_lshl_add_u64 v[8:9], v[8:9], 0, s[46:47]
	s_lshl_b32 s7, s7, 7
	v_lshl_add_u64 v[22:23], v[8:9], 0, v[52:53]
	global_load_dwordx4 v[8:11], v[20:21], off nt
	global_load_dwordx4 v[12:15], v[22:23], off offset:1024 nt
	v_lshlrev_b32_e32 v20, 7, v48
	s_or_b32 s6, s7, s6
	v_ashrrev_i32_e32 v21, 31, v20
	s_ashr_i32 s7, s6, 31
	v_lshlrev_b64 v[20:21], 1, v[20:21]
	s_lshl_b64 s[6:7], s[6:7], 15
	v_lshl_add_u64 v[24:25], v[16:17], 0, v[20:21]
	v_ashrrev_i32_e32 v49, 3, v63
	v_lshl_add_u64 v[26:27], v[18:19], 0, v[20:21]
	global_load_dwordx4 v[16:19], v[24:25], off nt
	global_load_dwordx4 v[20:23], v[26:27], off nt
	s_add_u32 s2, s38, s6
	v_lshlrev_b32_e32 v24, 6, v49
	s_addc_u32 s3, s39, s7
	v_ashrrev_i32_e32 v25, 31, v24
	v_add_u32_e32 v44, 0, v52
	v_add_u32_e32 v45, s50, v52
	v_add_u32_e32 v46, s51, v52
	v_lshl_add_u64 v[24:25], v[24:25], 1, s[2:3]
	v_and_b32_e32 v52, 0x70, v28
	v_lshl_add_u64 v[32:33], v[24:25], 0, v[52:53]
	v_add_co_u32_e32 v34, vcc, s55, v32
	v_readfirstlane_b32 s63, v63
	s_nop 0
	v_addc_co_u32_e32 v35, vcc, 0, v33, vcc
	global_load_dwordx4 v[24:27], v[32:33], off nt
	global_load_dwordx4 v[28:31], v[34:35], off nt
	v_add_co_u32_e32 v40, vcc, s56, v32
	v_and_b32_e32 v68, 31, v63
	s_nop 0
	v_addc_co_u32_e32 v41, vcc, 0, v33, vcc
	v_add_co_u32_e32 v42, vcc, s57, v32
	s_bfe_u32 s64, s63, 0x10006
	s_nop 0
	v_addc_co_u32_e32 v43, vcc, 0, v33, vcc
	global_load_dwordx4 v[32:35], v[40:41], off nt
	global_load_dwordx4 v[36:39], v[42:43], off nt
	v_mul_lo_u32 v40, v47, s53
	v_add_u32_e32 v41, v44, v40
	v_add_u32_e32 v42, v45, v40
	s_ashr_i32 s65, s63, 7
	s_lshl_b32 s48, s65, 5
	s_ashr_i32 s49, s48, 31
	s_bitcmp1_b32 s63, 6
	s_cselect_b64 s[36:37], -1, 0
	s_waitcnt vmcnt(0)
	ds_write_b128 v41, v[0:3] offset:45056
	ds_write_b128 v42, v[4:7]
	v_add_u32_e32 v0, v46, v40
	v_lshl_or_b32 v4, s64, 5, v68
	v_or_b32_e32 v62, s8, v4
	v_mad_u32_u24 v4, v4, s54, 0
	s_and_b64 vcc, exec, s[36:37]
	ds_write_b128 v0, v[8:11]
	v_mul_lo_u32 v0, v48, s53
	v_add_u32_e32 v1, v44, v0
	ds_write_b128 v1, v[12:15] offset:45056
	v_add_u32_e32 v1, v45, v0
	v_add_u32_e32 v0, v46, v0
	v_bfe_u32 v48, v63, 5, 1
	v_lshlrev_b32_e32 v5, 4, v48
	v_add_u32_e32 v87, v4, v5
	ds_write_b128 v1, v[16:19]
	ds_write_b128 v0, v[20:23]
	v_mul_lo_u32 v0, v49, s54
	v_add3_u32 v2, 0, v0, v52
	v_mad_i64_i32 v[0:1], s[2:3], v62, s52, v[54:55]
	v_lshl_add_u64 v[0:1], v[0:1], 0, s[46:47]
	v_lshl_add_u64 v[0:1], s[48:49], 1, v[0:1]
	v_lshlrev_b32_e32 v52, 3, v48
	ds_write_b128 v2, v[24:27] offset:8192
	ds_write_b128 v2, v[28:31] offset:17408
	v_lshl_add_u64 v[0:1], v[0:1], 0, v[52:53]
	global_load_dwordx2 v[64:65], v[0:1], off offset:2048
	global_load_dwordx2 v[60:61], v[0:1], off offset:2064
	global_load_dwordx2 v[58:59], v[0:1], off offset:2080
	global_load_dwordx2 v[56:57], v[0:1], off offset:2096
	v_add_u32_e32 v24, 0, v5
	v_mad_u32_u24 v25, v68, s54, v24
	ds_write_b128 v2, v[32:35] offset:26624
	ds_write_b128 v2, v[36:39] offset:35840
	s_waitcnt lgkmcnt(0)
	s_barrier
	ds_read_b128 v[0:3], v25 offset:17408
	ds_read_b128 v[44:47], v87 offset:8192
	ds_read_b128 v[40:43], v87 offset:8224
	ds_read_b128 v[4:7], v25 offset:17440
	s_waitcnt lgkmcnt(2)
	v_mfma_f32_32x32x16_bf16 v[8:23], v[0:3], v[44:47], 0
	v_lshlrev_b32_e32 v52, 2, v48
	v_or_b32_e32 v84, 2, v52
	v_or_b32_e32 v83, 3, v52
	v_or_b32_e32 v82, 8, v52
	v_or_b32_e32 v81, 9, v52
	v_or_b32_e32 v80, 10, v52
	v_or_b32_e32 v79, 11, v52
	s_waitcnt lgkmcnt(0)
	v_mfma_f32_32x32x16_bf16 v[8:23], v[4:7], v[40:43], v[8:23]
	ds_read_b128 v[0:3], v25 offset:17472
	ds_read_b128 v[36:39], v87 offset:8256
	ds_read_b128 v[32:35], v87 offset:8288
	ds_read_b128 v[4:7], v25 offset:17504
	v_or_b32_e32 v78, 16, v52
	v_or_b32_e32 v77, 17, v52
	v_or_b32_e32 v76, 18, v52
	v_or_b32_e32 v75, 19, v52
	v_or_b32_e32 v74, 24, v52
	v_or_b32_e32 v73, 25, v52
	s_waitcnt lgkmcnt(2)
	v_mfma_f32_32x32x16_bf16 v[8:23], v[0:3], v[36:39], v[8:23]
	v_or_b32_e32 v72, 26, v52
	v_or_b32_e32 v71, 27, v52
	v_cmp_le_u32_e64 s[2:3], v52, v68
	v_cmp_lt_u32_e64 s[4:5], v52, v68
	v_cmp_le_u32_e64 s[6:7], v84, v68
	v_cmp_le_u32_e64 s[8:9], v83, v68
	v_cmp_le_u32_e64 s[10:11], v82, v68
	s_waitcnt lgkmcnt(0)
	v_mfma_f32_32x32x16_bf16 v[8:23], v[4:7], v[32:35], v[8:23]
	v_cmp_le_u32_e64 s[12:13], v81, v68
	v_cmp_le_u32_e64 s[14:15], v80, v68
	v_cmp_le_u32_e64 s[16:17], v79, v68
	v_cmp_le_u32_e64 s[18:19], v78, v68
	v_cmp_le_u32_e64 s[20:21], v77, v68
	v_cmp_le_u32_e64 s[22:23], v76, v68
	v_cmp_le_u32_e64 s[24:25], v75, v68
	v_cmp_le_u32_e64 s[26:27], v74, v68
	v_cmp_le_u32_e64 s[28:29], v73, v68
	v_cmp_le_u32_e64 s[30:31], v72, v68
	v_cmp_le_u32_e64 s[34:35], v71, v68
	s_cbranch_vccnz .LBB0_507
	v_cndmask_b32_e64 v8, 0, v8, s[2:3]
	v_cndmask_b32_e64 v9, 0, v9, s[4:5]
	v_cndmask_b32_e64 v10, 0, v10, s[6:7]
	v_cndmask_b32_e64 v11, 0, v11, s[8:9]
	v_cndmask_b32_e64 v12, 0, v12, s[10:11]
	v_cndmask_b32_e64 v13, 0, v13, s[12:13]
	v_cndmask_b32_e64 v14, 0, v14, s[14:15]
	v_cndmask_b32_e64 v15, 0, v15, s[16:17]
	v_cndmask_b32_e64 v16, 0, v16, s[18:19]
	v_cndmask_b32_e64 v17, 0, v17, s[20:21]
	v_cndmask_b32_e64 v18, 0, v18, s[22:23]
	v_cndmask_b32_e64 v19, 0, v19, s[24:25]
	v_cndmask_b32_e64 v20, 0, v20, s[26:27]
	v_cndmask_b32_e64 v21, 0, v21, s[28:29]
	v_cndmask_b32_e64 v22, 0, v22, s[30:31]
	v_cndmask_b32_e64 v23, 0, v23, s[34:35]
